# scan loader waves touch the record and U lines four chunks ahead so the later 16-byte loads hit L2
# baseline (speedup 1.0000x reference)
; #define LAS __attribute__((address_space(3)))
; #define LDSBAR() do { asm volatile("s_waitcnt lgkmcnt(0)" ::: "memory"); __builtin_amdgcn_s_barrier(); asm volatile("" ::: "memory"); } while (0)
; DI void gdn_scan(const Args& a, int l, int bh, LAS unsigned char* lds, const int tidx, const bool nostore) {
;     ...
;     const unsigned char* rec = a.ws + WS_GREC + (size_t)bh * 64 * REC_BYTES;
;     const unsigned char* urec = a.ws + WS_UREC + (size_t)bh * 64 * 16384;
;     ...
;         const int pidx = tid - 256, sub = pidx & 15;
;         u32x4 pfa[14], pfb[14];
; #pragma unroll
;         for (int i = 0; i < 14; ++i) pfb[i] = *(const u32x4*)(rec + (size_t)(pidx + 256 * i) * 16);
; #pragma unroll
;         for (int i = 0; i < 14; ++i) pfa[i] = *(const u32x4*)(rec + REC_BYTES + (size_t)(pidx + 256 * i) * 16);
; #pragma unroll
;         for (int i = 0; i < 14; ++i) *(LAS u32x4*)(lds + (pidx + 256 * i) * 16) = pfb[i];
;         LDSBAR();
;         bf16_t* obase = proj + ((size_t)b * SEQ + (pidx >> 4)) * NPROJ + C_GV + h * 128 + sub * 8;
.LBB0_358:
	s_and_b64 vcc, exec, s[0:1]
	s_cbranch_vccz .LBB0_382
	v_readlane_b32 s0, v252, 30
	v_readlane_b32 s1, v252, 31
	s_andn2_b64 vcc, exec, s[0:1]
	s_cbranch_vccnz .LBB0_382
	v_readfirstlane_b32 s10, v220
	s_ashr_i32 s11, s10, 6
	s_ashr_i32 s97, s96, 31
	s_cmp_gt_i32 s11, 3
	s_mov_b64 s[0:1], -1
	s_cbranch_scc0 .LBB0_378
	s_mul_i32 s13, s96, 0x380000
	s_mul_hi_i32 s12, s96, 0x380000
	s_add_u32 s0, s58, s13
	s_addc_u32 s1, s59, s12
	v_add_u32_e32 v112, 0xffffff00, v220
	s_add_u32 s6, s0, 0x15500000
	v_ashrrev_i32_e32 v113, 31, v112
	s_addc_u32 s7, s1, 0
	v_lshlrev_b64 v[114:115], 4, v[112:113]
	v_lshlrev_b32_e32 v186, 7, v112
	v_mov_b32_e32 v187, 0
	s_lshl_b64 s[98:99], s[96:97], 20
	s_add_u32 s98, s98, s58
	s_addc_u32 s99, s99, s59
	s_add_u32 s98, s98, 0x1a900000
	s_addc_u32 s99, s99, 0
	v_lshl_add_u64 v[190:191], s[98:99], 0, v[186:187]
	v_lshl_add_u64 v[186:187], s[6:7], 0, v[186:187]
	s_mov_b64 s[100:101], 0x46000
	v_lshl_add_u64 v[186:187], v[186:187], 0, s[100:101]
	s_mov_b64 s[100:101], 0x8000
	v_lshl_add_u64 v[188:189], v[186:187], 0, s[100:101]
	s_mov_b64 s[100:101], 0x14000
	v_lshl_add_u64 v[190:191], v[190:191], 0, s[100:101]
	s_mov_b64 s[100:101], 0xe000
	s_mov_b64 s[98:99], 0x4000
	v_ashrrev_i32_e32 v221, 31, v220
	v_lshl_add_u64 v[0:1], s[6:7], 0, v[114:115]
	v_lshlrev_b64 v[116:117], 4, v[220:221]
	s_mov_b64 s[14:15], 0x1000
	global_load_dwordx4 v[0:3], v[0:1], off
	v_lshl_add_u64 v[4:5], s[6:7], 0, v[116:117]
	v_lshl_add_u64 v[118:119], v[116:117], 0, s[14:15]
	s_mov_b64 s[14:15], 0x2000
	global_load_dwordx4 v[4:7], v[4:5], off
	v_lshl_add_u64 v[8:9], s[6:7], 0, v[118:119]
	v_lshl_add_u64 v[120:121], v[116:117], 0, s[14:15]
	s_mov_b64 s[14:15], 0x3000
	global_load_dwordx4 v[8:11], v[8:9], off
	v_lshl_add_u64 v[12:13], s[6:7], 0, v[120:121]
	v_lshl_add_u64 v[122:123], v[116:117], 0, s[14:15]
	s_mov_b64 s[14:15], 0x4000
	global_load_dwordx4 v[12:15], v[12:13], off
	v_lshl_add_u64 v[16:17], s[6:7], 0, v[122:123]
	v_lshl_add_u64 v[124:125], v[116:117], 0, s[14:15]
	s_mov_b64 s[14:15], 0x5000
	global_load_dwordx4 v[16:19], v[16:17], off
	v_lshl_add_u64 v[20:21], s[6:7], 0, v[124:125]
	v_lshl_add_u64 v[126:127], v[116:117], 0, s[14:15]
	s_mov_b64 s[14:15], 0x6000
	global_load_dwordx4 v[20:23], v[20:21], off
	v_lshl_add_u64 v[24:25], s[6:7], 0, v[126:127]
	v_lshl_add_u64 v[128:129], v[116:117], 0, s[14:15]
	s_mov_b64 s[14:15], 0x7000
	global_load_dwordx4 v[24:27], v[24:25], off
	v_lshl_add_u64 v[28:29], s[6:7], 0, v[128:129]
	v_lshl_add_u64 v[130:131], v[116:117], 0, s[14:15]
	s_mov_b64 s[14:15], 0x8000
	global_load_dwordx4 v[28:31], v[28:29], off
	v_lshl_add_u64 v[32:33], s[6:7], 0, v[130:131]
	v_lshl_add_u64 v[132:133], v[116:117], 0, s[14:15]
	s_mov_b64 s[14:15], 0x9000
	global_load_dwordx4 v[32:35], v[32:33], off
	v_lshl_add_u64 v[36:37], s[6:7], 0, v[132:133]
	v_lshl_add_u64 v[134:135], v[116:117], 0, s[14:15]
	s_mov_b64 s[14:15], 0xa000
	global_load_dwordx4 v[36:39], v[36:37], off
	v_lshl_add_u64 v[40:41], s[6:7], 0, v[134:135]
	v_lshl_add_u64 v[136:137], v[116:117], 0, s[14:15]
	s_mov_b64 s[14:15], 0xb000
	global_load_dwordx4 v[40:43], v[40:41], off
	v_lshl_add_u64 v[44:45], s[6:7], 0, v[136:137]
	v_lshl_add_u64 v[138:139], v[116:117], 0, s[14:15]
	s_mov_b64 s[14:15], 0xc000
	global_load_dwordx4 v[44:47], v[44:45], off
	v_lshl_add_u64 v[48:49], s[6:7], 0, v[138:139]
	v_lshl_add_u64 v[140:141], v[116:117], 0, s[14:15]
	global_load_dwordx4 v[48:51], v[48:49], off
	v_lshl_add_u64 v[52:53], s[6:7], 0, v[140:141]
	global_load_dwordx4 v[52:55], v[52:53], off
	s_mul_hi_i32 s4, s96, 0x2aaaaaab
	s_lshr_b32 s5, s4, 31
	s_add_i32 s4, s4, s5
	s_mul_i32 s5, s4, 6
	s_sub_i32 s8, s96, s5
	s_add_u32 s14, s0, 0x1550e000
	s_addc_u32 s15, s1, 0
	s_ashr_i32 s5, s4, 31
	v_ashrrev_i32_e32 v142, 4, v112
	s_waitcnt vmcnt(0)
	v_lshl_add_u64 v[56:57], s[14:15], 0, v[114:115]
	v_lshl_add_u64 v[60:61], s[14:15], 0, v[116:117]
	v_lshl_add_u64 v[64:65], s[14:15], 0, v[118:119]
	v_lshl_add_u64 v[68:69], s[14:15], 0, v[120:121]
	v_lshl_add_u64 v[72:73], s[14:15], 0, v[122:123]
	v_lshl_add_u64 v[76:77], s[14:15], 0, v[124:125]
	v_lshl_add_u64 v[80:81], s[14:15], 0, v[126:127]
	v_lshl_add_u64 v[84:85], s[14:15], 0, v[128:129]
	v_lshl_add_u64 v[88:89], s[14:15], 0, v[130:131]
	v_lshl_add_u64 v[92:93], s[14:15], 0, v[132:133]
	v_lshl_add_u64 v[96:97], s[14:15], 0, v[134:135]
	v_lshl_add_u64 v[100:101], s[14:15], 0, v[136:137]
	v_lshl_add_u64 v[104:105], s[14:15], 0, v[138:139]
	v_lshl_add_u64 v[108:109], s[14:15], 0, v[140:141]
	v_lshl_add_u32 v174, v112, 4, 0
	s_lshl_b64 s[14:15], s[4:5], 12
	v_ashrrev_i32_e32 v143, 31, v142
	global_load_dwordx4 v[56:59], v[56:57], off
	s_lshl_b32 s8, s8, 7
	global_load_dwordx4 v[60:63], v[60:61], off
	s_ashr_i32 s9, s8, 31
	global_load_dwordx4 v[64:67], v[64:65], off
	s_add_i32 s5, 0, 0x1c000
	global_load_dwordx4 v[68:71], v[68:69], off
	s_add_u32 s0, s0, 0x1551c000
	global_load_dwordx4 v[72:75], v[72:73], off
	s_addc_u32 s1, s1, 0
	global_load_dwordx4 v[76:79], v[76:77], off
	v_add_u32_e32 v175, 0xe000, v174
	global_load_dwordx4 v[80:83], v[80:81], off
	s_nop 0
	global_load_dwordx4 v[84:87], v[84:85], off
	s_nop 0
	global_load_dwordx4 v[88:91], v[88:89], off
	s_nop 0
	global_load_dwordx4 v[92:95], v[92:93], off
	s_nop 0
	global_load_dwordx4 v[96:99], v[96:97], off
	s_nop 0
	global_load_dwordx4 v[100:103], v[100:101], off
	s_nop 0
	global_load_dwordx4 v[104:107], v[104:105], off
	s_nop 0
	global_load_dwordx4 v[108:111], v[108:109], off
	s_waitcnt vmcnt(27)
	ds_write_b128 v174, v[0:3]
	s_waitcnt vmcnt(26)
	ds_write_b128 v174, v[4:7] offset:4096
	s_waitcnt vmcnt(25)
	ds_write_b128 v174, v[8:11] offset:8192
	s_waitcnt vmcnt(24)
	ds_write_b128 v174, v[12:15] offset:12288
	s_waitcnt vmcnt(23)
	ds_write_b128 v174, v[16:19] offset:16384
	s_waitcnt vmcnt(22)
	ds_write_b128 v174, v[20:23] offset:20480
	s_waitcnt vmcnt(21)
	ds_write_b128 v174, v[24:27] offset:24576
	s_waitcnt vmcnt(20)
	ds_write_b128 v174, v[28:31] offset:28672
	s_waitcnt vmcnt(19)
	ds_write_b128 v174, v[32:35] offset:32768
	s_waitcnt vmcnt(18)
	ds_write_b128 v174, v[36:39] offset:36864
	s_waitcnt vmcnt(17)
	ds_write_b128 v174, v[40:43] offset:40960
	s_waitcnt vmcnt(16)
	ds_write_b128 v174, v[44:47] offset:45056
	s_waitcnt vmcnt(15)
	ds_write_b128 v174, v[48:51] offset:49152
	s_waitcnt vmcnt(14)
	ds_write_b128 v174, v[52:55] offset:53248
	v_lshl_add_u64 v[0:1], s[14:15], 0, v[142:143]
	v_mov_b64_e32 v[2:3], s[58:59]
	v_mad_u64_u32 v[2:3], s[14:15], v0, s47, v[2:3]
	v_mad_i32_i24 v3, v1, s47, v3
	v_lshl_add_u64 v[0:1], s[8:9], 1, v[2:3]
	v_lshlrev_b32_e32 v2, 3, v220
	v_and_b32_e32 v143, 0x78, v2
	v_lshlrev_b32_e32 v204, 1, v143
	v_lshl_add_u64 v[0:1], v[0:1], 0, v[204:205]
	s_mov_b64 s[14:15], 0x7d03000
	s_waitcnt lgkmcnt(0)
	s_barrier
; #define LAS __attribute__((address_space(3)))
; #define LDSBAR() do { asm volatile("s_waitcnt lgkmcnt(0)" ::: "memory"); __builtin_amdgcn_s_barrier(); asm volatile("" ::: "memory"); } while (0)
; DI void gdn_scan(const Args& a, int l, int bh, LAS unsigned char* lds, const int tidx, const bool nostore) {
;     ...
;         const int pidx = tid - 256, sub = pidx & 15;
;         u32x4 pfa[14], pfb[14];
; #pragma unroll
;         for (int i = 0; i < 14; ++i) pfb[i] = *(const u32x4*)(rec + (size_t)(pidx + 256 * i) * 16);
; #pragma unroll
;         for (int i = 0; i < 14; ++i) pfa[i] = *(const u32x4*)(rec + REC_BYTES + (size_t)(pidx + 256 * i) * 16);
; #pragma unroll
;         for (int i = 0; i < 14; ++i) *(LAS u32x4*)(lds + (pidx + 256 * i) * 16) = pfb[i];
;         LDSBAR();
;         bf16_t* obase = proj + ((size_t)b * SEQ + (pidx >> 4)) * NPROJ + C_GV + h * 128 + sub * 8;
;     ...
;         for (int n2 = 0; n2 < 64; n2 += 2) {
;             LOADER_ITER(n2, pfa, pfb);
;             LOADER_ITER(n2 + 1, pfb, pfa);
;         }
;         LOADER_ITER(64, pfa, pfb);
	v_lshl_add_u64 v[112:113], v[0:1], 0, s[14:15]
	v_lshl_add_u64 v[0:1], s[0:1], 0, v[114:115]
	v_lshl_add_u64 v[4:5], s[0:1], 0, v[116:117]
	v_lshl_add_u64 v[8:9], s[0:1], 0, v[118:119]
	v_lshl_add_u64 v[12:13], s[0:1], 0, v[120:121]
	v_lshl_add_u64 v[16:17], s[0:1], 0, v[122:123]
	v_lshl_add_u64 v[20:21], s[0:1], 0, v[124:125]
	v_lshl_add_u64 v[24:25], s[0:1], 0, v[126:127]
	v_lshl_add_u64 v[28:29], s[0:1], 0, v[128:129]
	v_lshl_add_u64 v[32:33], s[0:1], 0, v[130:131]
	v_lshl_add_u64 v[36:37], s[0:1], 0, v[132:133]
	v_lshl_add_u64 v[40:41], s[0:1], 0, v[134:135]
	v_lshl_add_u64 v[44:45], s[0:1], 0, v[136:137]
	v_lshl_add_u64 v[48:49], s[0:1], 0, v[138:139]
	v_lshl_add_u64 v[52:53], s[0:1], 0, v[140:141]
	global_load_dwordx4 v[0:3], v[0:1], off
	v_readlane_b32 s14, v252, 32
	global_load_dwordx4 v[4:7], v[4:5], off
	v_add_u32_e32 v144, s5, v204
	global_load_dwordx4 v[8:11], v[8:9], off
	s_movk_i32 s5, 0x110
	global_load_dwordx4 v[12:15], v[12:13], off
	v_readlane_b32 s15, v252, 33
	global_load_dwordx4 v[16:19], v[16:17], off
	v_mul_lo_u32 v176, v142, s5
	global_load_dwordx4 v[20:23], v[20:21], off
	s_andn2_b64 vcc, exec, s[14:15]
	global_load_dwordx4 v[24:27], v[24:25], off
	v_add_u32_e32 v177, v144, v176
	global_load_dwordx4 v[28:31], v[28:29], off
	s_nop 0
	global_load_dwordx4 v[32:35], v[32:33], off
	s_nop 0
	global_load_dwordx4 v[36:39], v[36:37], off
	s_nop 0
	global_load_dwordx4 v[40:43], v[40:41], off
	s_nop 0
	global_load_dwordx4 v[44:47], v[44:45], off
	s_nop 0
	global_load_dwordx4 v[48:51], v[48:49], off
	s_nop 0
	global_load_dwordx4 v[52:55], v[52:53], off
	s_waitcnt vmcnt(27)
	ds_write_b128 v174, v[56:59] offset:57344
	s_waitcnt vmcnt(26)
	ds_write_b128 v174, v[60:63] offset:61440
	s_waitcnt vmcnt(25)
	ds_write_b128 v175, v[64:67] offset:8192
	s_waitcnt vmcnt(24)
	ds_write_b128 v175, v[68:71] offset:12288
	s_waitcnt vmcnt(23)
	ds_write_b128 v175, v[72:75] offset:16384
	s_waitcnt vmcnt(22)
	ds_write_b128 v175, v[76:79] offset:20480
	s_waitcnt vmcnt(21)
	ds_write_b128 v175, v[80:83] offset:24576
	s_waitcnt vmcnt(20)
	ds_write_b128 v175, v[84:87] offset:28672
	s_waitcnt vmcnt(19)
	ds_write_b128 v175, v[88:91] offset:32768
	s_waitcnt vmcnt(18)
	ds_write_b128 v175, v[92:95] offset:36864
	s_waitcnt vmcnt(17)
	ds_write_b128 v175, v[96:99] offset:40960
	s_waitcnt vmcnt(16)
	ds_write_b128 v175, v[100:103] offset:45056
	s_waitcnt vmcnt(15)
	ds_write_b128 v175, v[104:107] offset:49152
	s_waitcnt vmcnt(14)
	ds_write_b128 v175, v[108:111] offset:53248
	s_waitcnt lgkmcnt(0)
	s_barrier
	v_cndmask_b32_e64 v56, 0, 1, s[14:15]
	v_cmp_ne_u32_e64 s[0:1], 1, v56
.LBB0_363:
	s_add_u32 s6, s6, 0x2a000
	s_addc_u32 s7, s7, 0
	v_lshl_add_u64 v[56:57], s[6:7], 0, v[114:115]
	v_lshl_add_u64 v[60:61], s[6:7], 0, v[116:117]
	v_lshl_add_u64 v[64:65], s[6:7], 0, v[118:119]
	v_lshl_add_u64 v[68:69], s[6:7], 0, v[120:121]
	v_lshl_add_u64 v[72:73], s[6:7], 0, v[122:123]
	v_lshl_add_u64 v[76:77], s[6:7], 0, v[124:125]
	v_lshl_add_u64 v[80:81], s[6:7], 0, v[126:127]
	v_lshl_add_u64 v[84:85], s[6:7], 0, v[128:129]
	v_lshl_add_u64 v[88:89], s[6:7], 0, v[130:131]
	v_lshl_add_u64 v[92:93], s[6:7], 0, v[132:133]
	v_lshl_add_u64 v[96:97], s[6:7], 0, v[134:135]
	v_lshl_add_u64 v[100:101], s[6:7], 0, v[136:137]
	v_lshl_add_u64 v[104:105], s[6:7], 0, v[138:139]
	v_lshl_add_u64 v[108:109], s[6:7], 0, v[140:141]
	global_load_dwordx4 v[56:59], v[56:57], off
	s_nop 0
	global_load_dwordx4 v[60:63], v[60:61], off
	s_nop 0
	global_load_dwordx4 v[64:67], v[64:65], off
	s_nop 0
	global_load_dwordx4 v[68:71], v[68:69], off
	s_nop 0
	global_load_dwordx4 v[72:75], v[72:73], off
	s_nop 0
	global_load_dwordx4 v[76:79], v[76:77], off
	s_nop 0
	global_load_dwordx4 v[80:83], v[80:81], off
	s_nop 0
	global_load_dwordx4 v[84:87], v[84:85], off
	s_nop 0
	global_load_dwordx4 v[88:91], v[88:89], off
	s_nop 0
	global_load_dwordx4 v[92:95], v[92:93], off
	s_nop 0
	global_load_dwordx4 v[96:99], v[96:97], off
	s_nop 0
	global_load_dwordx4 v[100:103], v[100:101], off
	s_nop 0
	global_load_dwordx4 v[104:107], v[104:105], off
	s_nop 0
	global_load_dwordx4 v[108:111], v[108:109], off
	global_load_dword v192, v[186:187], off
	global_load_dword v192, v[188:189], off
	global_load_dword v192, v[190:191], off
	v_lshl_add_u64 v[186:187], v[186:187], 0, s[100:101]
	v_lshl_add_u64 v[188:189], v[188:189], 0, s[100:101]
	v_lshl_add_u64 v[190:191], v[190:191], 0, s[98:99]
	s_add_u32 s6, s42, s13
	v_readlane_b32 s5, v254, 29
	s_addc_u32 s7, s43, s12
	v_lshl_add_u64 v[114:115], s[6:7], 0, v[114:115]
	v_lshl_add_u32 v144, v143, 1, s5
	v_lshl_add_u64 v[116:117], s[6:7], 0, v[116:117]
	v_lshl_add_u64 v[118:119], s[6:7], 0, v[118:119]
	v_lshl_add_u64 v[120:121], s[6:7], 0, v[120:121]
	v_lshl_add_u64 v[122:123], s[6:7], 0, v[122:123]
	v_lshl_add_u64 v[124:125], s[6:7], 0, v[124:125]
	v_lshl_add_u64 v[126:127], s[6:7], 0, v[126:127]
	v_lshl_add_u64 v[128:129], s[6:7], 0, v[128:129]
	v_lshl_add_u64 v[130:131], s[6:7], 0, v[130:131]
	v_lshl_add_u64 v[132:133], s[6:7], 0, v[132:133]
	v_lshl_add_u64 v[134:135], s[6:7], 0, v[134:135]
	v_lshl_add_u64 v[136:137], s[6:7], 0, v[136:137]
	v_lshl_add_u64 v[138:139], s[6:7], 0, v[138:139]
	v_lshl_add_u64 v[140:141], s[6:7], 0, v[140:141]
	v_mad_i64_i32 v[142:143], s[6:7], v142, s47, 0
	v_mad_i64_i32 v[142:143], s[4:5], s4, v243, v[142:143]
	s_waitcnt vmcnt(27)
	ds_write_b128 v174, v[0:3]
	s_waitcnt vmcnt(26)
	ds_write_b128 v174, v[4:7] offset:4096
	s_waitcnt vmcnt(25)
	ds_write_b128 v174, v[8:11] offset:8192
	s_waitcnt vmcnt(24)
	ds_write_b128 v174, v[12:15] offset:12288
	s_waitcnt vmcnt(23)
	ds_write_b128 v174, v[16:19] offset:16384
	s_waitcnt vmcnt(22)
	ds_write_b128 v174, v[20:23] offset:20480
	s_waitcnt vmcnt(21)
	ds_write_b128 v174, v[24:27] offset:24576
	s_waitcnt vmcnt(20)
	ds_write_b128 v174, v[28:31] offset:28672
	s_waitcnt vmcnt(19)
	ds_write_b128 v174, v[32:35] offset:32768
	s_waitcnt vmcnt(18)
	ds_write_b128 v174, v[36:39] offset:36864
	s_waitcnt vmcnt(17)
	ds_write_b128 v174, v[40:43] offset:40960
	s_waitcnt vmcnt(16)
	ds_write_b128 v174, v[44:47] offset:45056
	s_waitcnt vmcnt(15)
	ds_write_b128 v174, v[48:51] offset:49152
	s_waitcnt vmcnt(14)
	ds_write_b128 v174, v[52:55] offset:53248
	s_and_b64 vcc, exec, s[0:1]
	s_cbranch_vccnz .Lldr_p1_st_done
	ds_read_b128 v[180:183], v177
	v_add_co_u32_e32 v184, vcc, 0x36000, v112
	s_waitcnt lgkmcnt(0)
	global_store_dwordx4 v[112:113], v[180:183], off
	ds_read_b128 v[180:183], v177 offset:4352
	v_addc_co_u32_e32 v185, vcc, 0, v113, vcc
	s_waitcnt lgkmcnt(0)
	global_store_dwordx4 v[184:185], v[180:183], off
	ds_read_b128 v[180:183], v177 offset:8704
	v_add_co_u32_e32 v184, vcc, 0x6c000, v112
	s_nop 1
	v_addc_co_u32_e32 v185, vcc, 0, v113, vcc
	s_waitcnt lgkmcnt(0)
	global_store_dwordx4 v[184:185], v[180:183], off
	ds_read_b128 v[180:183], v177 offset:13056
	v_add_co_u32_e32 v184, vcc, 0xa2000, v112
	s_nop 1
	v_addc_co_u32_e32 v185, vcc, 0, v113, vcc
	s_waitcnt lgkmcnt(0)
	global_store_dwordx4 v[184:185], v[180:183], off

; DI void gdn_scan(const Args& a, int l, int bh, LAS unsigned char* lds, const int tidx, const bool nostore) {
;     ...
;         for (int n2 = 0; n2 < 64; n2 += 2) {
;             LOADER_ITER(n2, pfa, pfb);
;             LOADER_ITER(n2 + 1, pfb, pfa);
;         }
.LBB0_367:
	s_cmp_gt_u32 s6, 61
	s_cselect_b64 s[4:5], -1, 0
	s_and_b64 vcc, exec, s[4:5]
	v_lshl_add_u64 v[172:173], v[114:115], 0, s[94:95]
	v_lshl_add_u64 v[170:171], v[116:117], 0, s[94:95]
	v_lshl_add_u64 v[168:169], v[118:119], 0, s[94:95]
	v_lshl_add_u64 v[166:167], v[120:121], 0, s[94:95]
	v_lshl_add_u64 v[164:165], v[122:123], 0, s[94:95]
	v_lshl_add_u64 v[160:161], v[124:125], 0, s[94:95]
	v_lshl_add_u64 v[158:159], v[126:127], 0, s[94:95]
	v_lshl_add_u64 v[156:157], v[128:129], 0, s[94:95]
	v_lshl_add_u64 v[154:155], v[130:131], 0, s[94:95]
	v_lshl_add_u64 v[152:153], v[132:133], 0, s[94:95]
	v_lshl_add_u64 v[150:151], v[134:135], 0, s[94:95]
	v_lshl_add_u64 v[148:149], v[136:137], 0, s[94:95]
	v_lshl_add_u64 v[146:147], v[138:139], 0, s[94:95]
	v_lshl_add_u64 v[144:145], v[140:141], 0, s[94:95]
	s_cbranch_vccnz .LBB0_369
	v_add_co_u32_e32 v0, vcc, 0x15538000, v172
	s_nop 1
	v_addc_co_u32_e32 v1, vcc, 0, v173, vcc
	v_add_co_u32_e32 v4, vcc, 0x15538000, v170
	global_load_dwordx4 v[0:3], v[0:1], off
	s_nop 0
	v_addc_co_u32_e32 v5, vcc, 0, v171, vcc
	v_add_co_u32_e32 v8, vcc, 0x15538000, v168
	global_load_dwordx4 v[4:7], v[4:5], off
	s_nop 0
	v_addc_co_u32_e32 v9, vcc, 0, v169, vcc
	v_add_co_u32_e32 v12, vcc, 0x15538000, v166
	global_load_dwordx4 v[8:11], v[8:9], off
	s_nop 0
	v_addc_co_u32_e32 v13, vcc, 0, v167, vcc
	v_add_co_u32_e32 v16, vcc, 0x15538000, v164
	global_load_dwordx4 v[12:15], v[12:13], off
	s_nop 0
	v_addc_co_u32_e32 v17, vcc, 0, v165, vcc
	v_add_co_u32_e32 v20, vcc, 0x15538000, v160
	global_load_dwordx4 v[16:19], v[16:17], off
	s_nop 0
	v_addc_co_u32_e32 v21, vcc, 0, v161, vcc
	v_add_co_u32_e32 v24, vcc, 0x15538000, v158
	global_load_dwordx4 v[20:23], v[20:21], off
	s_nop 0
	v_addc_co_u32_e32 v25, vcc, 0, v159, vcc
	v_add_co_u32_e32 v28, vcc, 0x15538000, v156
	global_load_dwordx4 v[24:27], v[24:25], off
	s_nop 0
	v_addc_co_u32_e32 v29, vcc, 0, v157, vcc
	v_add_co_u32_e32 v32, vcc, 0x15538000, v154
	global_load_dwordx4 v[28:31], v[28:29], off
	s_nop 0
	v_addc_co_u32_e32 v33, vcc, 0, v155, vcc
	v_add_co_u32_e32 v36, vcc, 0x15538000, v152
	global_load_dwordx4 v[32:35], v[32:33], off
	s_nop 0
	v_addc_co_u32_e32 v37, vcc, 0, v153, vcc
	v_add_co_u32_e32 v40, vcc, 0x15538000, v150
	global_load_dwordx4 v[36:39], v[36:37], off
	s_nop 0
	v_addc_co_u32_e32 v41, vcc, 0, v151, vcc
	v_add_co_u32_e32 v44, vcc, 0x15538000, v148
	global_load_dwordx4 v[40:43], v[40:41], off
	s_nop 0
	v_addc_co_u32_e32 v45, vcc, 0, v149, vcc
	v_add_co_u32_e32 v48, vcc, 0x15538000, v146
	global_load_dwordx4 v[44:47], v[44:45], off
	s_nop 0
	v_addc_co_u32_e32 v49, vcc, 0, v147, vcc
	v_add_co_u32_e32 v52, vcc, 0x15538000, v144
	global_load_dwordx4 v[48:51], v[48:49], off
	s_nop 0
	v_addc_co_u32_e32 v53, vcc, 0, v145, vcc
	global_load_dwordx4 v[52:55], v[52:53], off
	global_load_dword v192, v[186:187], off
	global_load_dword v192, v[188:189], off
	global_load_dword v192, v[190:191], off
	v_lshl_add_u64 v[186:187], v[186:187], 0, s[100:101]
	v_lshl_add_u64 v[188:189], v[188:189], 0, s[100:101]
	v_lshl_add_u64 v[190:191], v[190:191], 0, s[98:99]
	s_and_b64 vcc, exec, s[0:1]
	s_cbranch_vccnz .Lldr_even_A27
	s_waitcnt vmcnt(37)
	ds_write_b128 v174, v[56:59] offset:57344
	s_waitcnt vmcnt(36)
	ds_write_b128 v174, v[60:63] offset:61440
	s_waitcnt vmcnt(35)
	ds_write_b128 v175, v[64:67] offset:8192
	s_waitcnt vmcnt(34)
	ds_write_b128 v175, v[68:71] offset:12288
	s_waitcnt vmcnt(33)
	ds_write_b128 v175, v[72:75] offset:16384
	s_waitcnt vmcnt(32)
	ds_write_b128 v175, v[76:79] offset:20480
	s_waitcnt vmcnt(31)
	ds_write_b128 v175, v[80:83] offset:24576
	s_waitcnt vmcnt(30)
	ds_write_b128 v175, v[84:87] offset:28672
	s_waitcnt vmcnt(29)
	ds_write_b128 v175, v[88:91] offset:32768
	s_waitcnt vmcnt(28)
	ds_write_b128 v175, v[92:95] offset:36864
	s_waitcnt vmcnt(27)
	ds_write_b128 v175, v[96:99] offset:40960
	s_waitcnt vmcnt(26)
	ds_write_b128 v175, v[100:103] offset:45056
	s_waitcnt vmcnt(25)
	ds_write_b128 v175, v[104:107] offset:49152
	s_waitcnt vmcnt(24)
	ds_write_b128 v175, v[108:111] offset:53248
	s_branch .Lldr_even_wr_done
.Lldr_even_A27:
	s_waitcnt vmcnt(33)
	ds_write_b128 v174, v[56:59] offset:57344
	s_waitcnt vmcnt(32)
	ds_write_b128 v174, v[60:63] offset:61440
	s_waitcnt vmcnt(31)
	ds_write_b128 v175, v[64:67] offset:8192
	s_waitcnt vmcnt(30)
	ds_write_b128 v175, v[68:71] offset:12288
	s_waitcnt vmcnt(29)
	ds_write_b128 v175, v[72:75] offset:16384
	s_waitcnt vmcnt(28)
	ds_write_b128 v175, v[76:79] offset:20480
	s_waitcnt vmcnt(27)
	ds_write_b128 v175, v[80:83] offset:24576
	s_waitcnt vmcnt(26)
	ds_write_b128 v175, v[84:87] offset:28672
	s_waitcnt vmcnt(25)
	ds_write_b128 v175, v[88:91] offset:32768
	s_waitcnt vmcnt(24)
	ds_write_b128 v175, v[92:95] offset:36864
	s_waitcnt vmcnt(23)
	ds_write_b128 v175, v[96:99] offset:40960
	s_waitcnt vmcnt(22)
	ds_write_b128 v175, v[100:103] offset:45056
	s_waitcnt vmcnt(21)
	ds_write_b128 v175, v[104:107] offset:49152
	s_waitcnt vmcnt(20)
	ds_write_b128 v175, v[108:111] offset:53248
	s_branch .Lldr_even_wr_done

; DI void gdn_scan(const Args& a, int l, int bh, LAS unsigned char* lds, const int tidx, const bool nostore) {
;     ...
;         for (int n2 = 0; n2 < 64; n2 += 2) {
;             LOADER_ITER(n2, pfa, pfb);
;             LOADER_ITER(n2 + 1, pfb, pfa);
;         }
.LBB0_373:
	v_add_co_u32_e32 v56, vcc, 0x15546000, v172
	s_nop 1
	v_addc_co_u32_e32 v57, vcc, 0, v173, vcc
	v_add_co_u32_e32 v60, vcc, 0x15546000, v170
	global_load_dwordx4 v[56:59], v[56:57], off
	s_nop 0
	v_addc_co_u32_e32 v61, vcc, 0, v171, vcc
	v_add_co_u32_e32 v64, vcc, 0x15546000, v168
	global_load_dwordx4 v[60:63], v[60:61], off
	s_nop 0
	v_addc_co_u32_e32 v65, vcc, 0, v169, vcc
	v_add_co_u32_e32 v68, vcc, 0x15546000, v166
	global_load_dwordx4 v[64:67], v[64:65], off
	s_nop 0
	v_addc_co_u32_e32 v69, vcc, 0, v167, vcc
	v_add_co_u32_e32 v72, vcc, 0x15546000, v164
	global_load_dwordx4 v[68:71], v[68:69], off
	s_nop 0
	v_addc_co_u32_e32 v73, vcc, 0, v165, vcc
	v_add_co_u32_e32 v76, vcc, 0x15546000, v160
	global_load_dwordx4 v[72:75], v[72:73], off
	s_nop 0
	v_addc_co_u32_e32 v77, vcc, 0, v161, vcc
	v_add_co_u32_e32 v80, vcc, 0x15546000, v158
	global_load_dwordx4 v[76:79], v[76:77], off
	s_nop 0
	v_addc_co_u32_e32 v81, vcc, 0, v159, vcc
	v_add_co_u32_e32 v84, vcc, 0x15546000, v156
	global_load_dwordx4 v[80:83], v[80:81], off
	s_nop 0
	v_addc_co_u32_e32 v85, vcc, 0, v157, vcc
	v_add_co_u32_e32 v88, vcc, 0x15546000, v154
	global_load_dwordx4 v[84:87], v[84:85], off
	s_nop 0
	v_addc_co_u32_e32 v89, vcc, 0, v155, vcc
	v_add_co_u32_e32 v92, vcc, 0x15546000, v152
	global_load_dwordx4 v[88:91], v[88:89], off
	s_nop 0
	v_addc_co_u32_e32 v93, vcc, 0, v153, vcc
	v_add_co_u32_e32 v96, vcc, 0x15546000, v150
	global_load_dwordx4 v[92:95], v[92:93], off
	s_nop 0
	v_addc_co_u32_e32 v97, vcc, 0, v151, vcc
	v_add_co_u32_e32 v100, vcc, 0x15546000, v148
	global_load_dwordx4 v[96:99], v[96:97], off
	s_nop 0
	v_addc_co_u32_e32 v101, vcc, 0, v149, vcc
	v_add_co_u32_e32 v104, vcc, 0x15546000, v146
	global_load_dwordx4 v[100:103], v[100:101], off
	s_nop 0
	v_addc_co_u32_e32 v105, vcc, 0, v147, vcc
	v_add_co_u32_e32 v108, vcc, 0x15546000, v144
	global_load_dwordx4 v[104:107], v[104:105], off
	s_nop 0
	v_addc_co_u32_e32 v109, vcc, 0, v145, vcc
	global_load_dwordx4 v[108:111], v[108:109], off
	global_load_dword v192, v[186:187], off
	global_load_dword v192, v[188:189], off
	global_load_dword v192, v[190:191], off
	v_lshl_add_u64 v[186:187], v[186:187], 0, s[100:101]
	v_lshl_add_u64 v[188:189], v[188:189], 0, s[100:101]
	v_lshl_add_u64 v[190:191], v[190:191], 0, s[98:99]
	s_and_b64 vcc, exec, s[0:1]
	s_cbranch_vccnz .Lldr_odd_A27
	s_waitcnt vmcnt(37)
	ds_write_b128 v174, v[0:3]
	s_waitcnt vmcnt(36)
	ds_write_b128 v174, v[4:7] offset:4096
	s_waitcnt vmcnt(35)
	ds_write_b128 v174, v[8:11] offset:8192
	s_waitcnt vmcnt(34)
	ds_write_b128 v174, v[12:15] offset:12288
	s_waitcnt vmcnt(33)
	ds_write_b128 v174, v[16:19] offset:16384
	s_waitcnt vmcnt(32)
	ds_write_b128 v174, v[20:23] offset:20480
	s_waitcnt vmcnt(31)
	ds_write_b128 v174, v[24:27] offset:24576
	s_waitcnt vmcnt(30)
	ds_write_b128 v174, v[28:31] offset:28672
	s_waitcnt vmcnt(29)
	ds_write_b128 v174, v[32:35] offset:32768
	s_waitcnt vmcnt(28)
	ds_write_b128 v174, v[36:39] offset:36864
	s_waitcnt vmcnt(27)
	ds_write_b128 v174, v[40:43] offset:40960
	s_waitcnt vmcnt(26)
	ds_write_b128 v174, v[44:47] offset:45056
	s_waitcnt vmcnt(25)
	ds_write_b128 v174, v[48:51] offset:49152
	s_waitcnt vmcnt(24)
	ds_write_b128 v174, v[52:55] offset:53248
	s_branch .Lldr_odd_wr_done
.Lldr_odd_A27:
	s_waitcnt vmcnt(33)
	ds_write_b128 v174, v[0:3]
	s_waitcnt vmcnt(32)
	ds_write_b128 v174, v[4:7] offset:4096
	s_waitcnt vmcnt(31)
	ds_write_b128 v174, v[8:11] offset:8192
	s_waitcnt vmcnt(30)
	ds_write_b128 v174, v[12:15] offset:12288
	s_waitcnt vmcnt(29)
	ds_write_b128 v174, v[16:19] offset:16384
	s_waitcnt vmcnt(28)
	ds_write_b128 v174, v[20:23] offset:20480
	s_waitcnt vmcnt(27)
	ds_write_b128 v174, v[24:27] offset:24576
	s_waitcnt vmcnt(26)
	ds_write_b128 v174, v[28:31] offset:28672
	s_waitcnt vmcnt(25)
	ds_write_b128 v174, v[32:35] offset:32768
	s_waitcnt vmcnt(24)
	ds_write_b128 v174, v[36:39] offset:36864
	s_waitcnt vmcnt(23)
	ds_write_b128 v174, v[40:43] offset:40960
	s_waitcnt vmcnt(22)
	ds_write_b128 v174, v[44:47] offset:45056
	s_waitcnt vmcnt(21)
	ds_write_b128 v174, v[48:51] offset:49152
	s_waitcnt vmcnt(20)
	ds_write_b128 v174, v[52:55] offset:53248
